# grid barriers: waiting workgroups also poll the TOP arrival counter directly instead of their XCD's release counter (no leader relay hop)
# speedup vs baseline: 1.0065x; 1.0032x over previous
; __device__ __forceinline__ unsigned xb_ld(unsigned* p)              { return __hip_atomic_load(p, __ATOMIC_RELAXED, __HIP_MEMORY_SCOPE_AGENT); }
; __device__ __forceinline__ unsigned xb_add(unsigned* p, unsigned v) { return __hip_atomic_fetch_add(p, v, __ATOMIC_RELAXED, __HIP_MEMORY_SCOPE_AGENT); }
; #define XB_SPIN(cond, bar) do { unsigned _sp = 0; while (cond) { __builtin_amdgcn_s_sleep(1); \
;     if ((++_sp & 255u) == 0u) { if (xb_ld(&(bar)[XB_TMO])) break; if (_sp > XB_SPIN_CAP) { atomicAdd(&(bar)[XB_TMO], 1u); break; } } } } while (0)
; __device__ __forceinline__ void xcd_barrier(const XcdBarrier& b) {
;     ...
;         const unsigned old = xb_add(&bar[XB_XSUB(b.x)], 1u);
;         const unsigned gen = old / nloc;
;         if (old + 1u == (gen + 1u) * nloc) {
;             __builtin_amdgcn_fence(__ATOMIC_RELEASE, "agent");
;             asm volatile("s_waitcnt vmcnt(0)" ::: "memory");
;             const unsigned og = xb_add(&bar[XB_TOP], 1u);
;             const unsigned tg = og / nx;
;             if (og + 1u == (tg + 1u) * nx) xb_add(&bar[XB_TOPGEN], 1u);
;             else XB_SPIN(xb_ld(&bar[XB_TOPGEN]) == tg, bar);
;             __builtin_amdgcn_fence(__ATOMIC_ACQUIRE, "agent");
;             xb_add(&bar[XB_XGEN(b.x)], 1u);
;             asm volatile("s_waitcnt vmcnt(0)" ::: "memory");
;         } else {
;             XB_SPIN(xb_ld(&bar[XB_XGEN(b.x)]) == gen, bar);
;             __builtin_amdgcn_fence(__ATOMIC_ACQUIRE, "agent");
.LBB0_149:
	s_or_b64 exec, exec, s[10:11]
	v_cvt_f32_u32_e32 v4, v2
	s_waitcnt vmcnt(0)
	v_readfirstlane_b32 s8, v3
	v_sub_u32_e32 v3, 0, v2
	v_rcp_iflag_f32_e32 v4, v4
	v_add_u32_e32 v5, s8, v1
	v_mul_f32_e32 v4, 0x4f7ffffe, v4
	v_cvt_u32_f32_e32 v4, v4
	v_mul_lo_u32 v1, v3, v4
	v_mul_hi_u32 v1, v4, v1
	v_add_u32_e32 v1, v4, v1
	v_mul_hi_u32 v1, v5, v1
	v_mul_lo_u32 v3, v1, v2
	v_sub_u32_e32 v3, v5, v3
	v_add_u32_e32 v4, 1, v1
	v_cmp_ge_u32_e32 vcc, v3, v2
	s_nop 1
	v_cndmask_b32_e32 v1, v1, v4, vcc
	v_sub_u32_e32 v4, v3, v2
	v_cndmask_b32_e32 v3, v3, v4, vcc
	v_add_u32_e32 v4, 1, v1
	v_cmp_ge_u32_e32 vcc, v3, v2
	v_add_u32_e32 v3, 1, v5
	s_nop 0
	v_cndmask_b32_e32 v1, v1, v4, vcc
	v_mul_lo_u32 v4, v2, v1
	v_add_u32_e32 v2, v4, v2
	v_cmp_ne_u32_e32 vcc, v3, v2
	s_and_saveexec_b64 s[8:9], vcc
	s_xor_b64 s[8:9], exec, s[8:9]
	s_cbranch_execz .LBB0_163
	s_waitcnt lgkmcnt(0)
	v_add_u32_e32 v4, 1, v1
	v_mul_lo_u32 v4, v4, v0
	v_mov_b32_e32 v5, 0x2303000
	v_mov_b32_e32 v0, 0x2000
	buffer_inv sc1
	global_load_dword v0, v5, s[70:71] offset:1024 sc1
	s_add_u32 s18, s6, 0x2400
	s_addc_u32 s19, s7, 0
	s_waitcnt vmcnt(0)
	v_cmp_lt_u32_e32 vcc, v0, v4
	s_and_saveexec_b64 s[10:11], vcc
	s_cbranch_execz .LBB0_162
	s_add_u32 s12, s70, 0x2300200
	s_addc_u32 s13, s71, 0
	s_mov_b32 s14, 1
	s_mov_b64 s[20:21], 0
	v_mov_b32_e32 v0, 0
	s_branch .LBB0_153

.LBB0_157:
	global_load_dword v2, v5, s[70:71] offset:1024 sc1
	s_add_i32 s14, s14, 1
	s_mov_b64 s[48:49], -1
	s_waitcnt vmcnt(0)
	v_cmp_ge_u32_e32 vcc, v2, v4
	s_orn2_b64 s[46:47], vcc, exec
	s_branch .LBB0_152

; __device__ __forceinline__ unsigned xb_ld(unsigned* p)              { return __hip_atomic_load(p, __ATOMIC_RELAXED, __HIP_MEMORY_SCOPE_AGENT); }
; __device__ __forceinline__ unsigned xb_add(unsigned* p, unsigned v) { return __hip_atomic_fetch_add(p, v, __ATOMIC_RELAXED, __HIP_MEMORY_SCOPE_AGENT); }
; #define XB_SPIN(cond, bar) do { unsigned _sp = 0; while (cond) { __builtin_amdgcn_s_sleep(1); \
;     if ((++_sp & 255u) == 0u) { if (xb_ld(&(bar)[XB_TMO])) break; if (_sp > XB_SPIN_CAP) { atomicAdd(&(bar)[XB_TMO], 1u); break; } } } } while (0)
; __device__ __forceinline__ void xcd_barrier(const XcdBarrier& b) {
;     ...
;         const unsigned old = xb_add(&bar[XB_XSUB(b.x)], 1u);
;         const unsigned gen = old / nloc;
;         if (old + 1u == (gen + 1u) * nloc) {
;             __builtin_amdgcn_fence(__ATOMIC_RELEASE, "agent");
;             asm volatile("s_waitcnt vmcnt(0)" ::: "memory");
;             const unsigned og = xb_add(&bar[XB_TOP], 1u);
;             const unsigned tg = og / nx;
;             if (og + 1u == (tg + 1u) * nx) xb_add(&bar[XB_TOPGEN], 1u);
;             else XB_SPIN(xb_ld(&bar[XB_TOPGEN]) == tg, bar);
;             __builtin_amdgcn_fence(__ATOMIC_ACQUIRE, "agent");
;             xb_add(&bar[XB_XGEN(b.x)], 1u);
;             asm volatile("s_waitcnt vmcnt(0)" ::: "memory");
;         } else {
;             XB_SPIN(xb_ld(&bar[XB_XGEN(b.x)]) == gen, bar);
;             __builtin_amdgcn_fence(__ATOMIC_ACQUIRE, "agent");
.LBB0_242:
	s_or_b64 exec, exec, s[8:9]
	v_cvt_f32_u32_e32 v4, v2
	s_waitcnt vmcnt(0)
	v_readfirstlane_b32 s6, v3
	v_sub_u32_e32 v3, 0, v2
	v_rcp_iflag_f32_e32 v4, v4
	v_add_u32_e32 v5, s6, v1
	v_mul_f32_e32 v4, 0x4f7ffffe, v4
	v_cvt_u32_f32_e32 v4, v4
	v_mul_lo_u32 v1, v3, v4
	v_mul_hi_u32 v1, v4, v1
	v_add_u32_e32 v1, v4, v1
	v_mul_hi_u32 v1, v5, v1
	v_mul_lo_u32 v3, v1, v2
	v_sub_u32_e32 v3, v5, v3
	v_add_u32_e32 v4, 1, v1
	v_cmp_ge_u32_e32 vcc, v3, v2
	s_nop 1
	v_cndmask_b32_e32 v1, v1, v4, vcc
	v_sub_u32_e32 v4, v3, v2
	v_cndmask_b32_e32 v3, v3, v4, vcc
	v_add_u32_e32 v4, 1, v1
	v_cmp_ge_u32_e32 vcc, v3, v2
	v_add_u32_e32 v3, 1, v5
	s_nop 0
	v_cndmask_b32_e32 v1, v1, v4, vcc
	v_mul_lo_u32 v4, v2, v1
	v_add_u32_e32 v2, v4, v2
	v_cmp_ne_u32_e32 vcc, v3, v2
	s_and_saveexec_b64 s[6:7], vcc
	s_xor_b64 s[6:7], exec, s[6:7]
	s_cbranch_execz .LBB0_256
	s_waitcnt lgkmcnt(0)
	v_add_u32_e32 v4, 1, v1
	v_mul_lo_u32 v4, v4, v0
	v_mov_b32_e32 v5, 0x2303000
	v_mov_b32_e32 v0, 0x2000
	buffer_inv sc1
	global_load_dword v0, v5, s[70:71] offset:1024 sc1
	s_add_u32 s12, s4, 0x2400
	s_addc_u32 s13, s5, 0
	s_waitcnt vmcnt(0)
	v_cmp_lt_u32_e32 vcc, v0, v4
	s_and_saveexec_b64 s[8:9], vcc
	s_cbranch_execz .LBB0_255
	s_add_u32 s10, s70, 0x2300200
	s_addc_u32 s11, s71, 0
	s_mov_b32 s14, 1
	s_mov_b64 s[18:19], 0
	v_mov_b32_e32 v0, 0
	s_branch .LBB0_246

.LBB0_250:
	global_load_dword v2, v5, s[70:71] offset:1024 sc1
	s_add_i32 s14, s14, 1
	s_mov_b64 s[46:47], -1
	s_waitcnt vmcnt(0)
	v_cmp_ge_u32_e32 vcc, v2, v4
	s_orn2_b64 s[28:29], vcc, exec
	s_branch .LBB0_245

.LBB0_317:
	global_load_dword v2, v5, s[70:71] offset:1024 sc1
	s_add_i32 s14, s14, 1
	s_mov_b64 s[26:27], -1
	s_waitcnt vmcnt(0)
	v_cmp_ge_u32_e32 vcc, v2, v4
	s_orn2_b64 s[24:25], vcc, exec
	s_branch .LBB0_312

; __device__ __forceinline__ unsigned xb_ld(unsigned* p)              { return __hip_atomic_load(p, __ATOMIC_RELAXED, __HIP_MEMORY_SCOPE_AGENT); }
; __device__ __forceinline__ unsigned xb_add(unsigned* p, unsigned v) { return __hip_atomic_fetch_add(p, v, __ATOMIC_RELAXED, __HIP_MEMORY_SCOPE_AGENT); }
; #define XB_SPIN(cond, bar) do { unsigned _sp = 0; while (cond) { __builtin_amdgcn_s_sleep(1); \
;     if ((++_sp & 255u) == 0u) { if (xb_ld(&(bar)[XB_TMO])) break; if (_sp > XB_SPIN_CAP) { atomicAdd(&(bar)[XB_TMO], 1u); break; } } } } while (0)
; __device__ __forceinline__ void xcd_barrier(const XcdBarrier& b) {
;     ...
;         const unsigned old = xb_add(&bar[XB_XSUB(b.x)], 1u);
;         const unsigned gen = old / nloc;
;         if (old + 1u == (gen + 1u) * nloc) {
;             __builtin_amdgcn_fence(__ATOMIC_RELEASE, "agent");
;             asm volatile("s_waitcnt vmcnt(0)" ::: "memory");
;             const unsigned og = xb_add(&bar[XB_TOP], 1u);
;             const unsigned tg = og / nx;
;             if (og + 1u == (tg + 1u) * nx) xb_add(&bar[XB_TOPGEN], 1u);
;             else XB_SPIN(xb_ld(&bar[XB_TOPGEN]) == tg, bar);
;             __builtin_amdgcn_fence(__ATOMIC_ACQUIRE, "agent");
;             xb_add(&bar[XB_XGEN(b.x)], 1u);
;             asm volatile("s_waitcnt vmcnt(0)" ::: "memory");
;         } else {
;             XB_SPIN(xb_ld(&bar[XB_XGEN(b.x)]) == gen, bar);
;             __builtin_amdgcn_fence(__ATOMIC_ACQUIRE, "agent");
.LBB0_785:
	s_or_b64 exec, exec, s[10:11]
	v_cvt_f32_u32_e32 v4, v2
	s_waitcnt vmcnt(0)
	v_readfirstlane_b32 s3, v3
	v_sub_u32_e32 v3, 0, v2
	v_rcp_iflag_f32_e32 v4, v4
	v_add_u32_e32 v5, s3, v1
	v_mul_f32_e32 v4, 0x4f7ffffe, v4
	v_cvt_u32_f32_e32 v4, v4
	v_mul_lo_u32 v1, v3, v4
	v_mul_hi_u32 v1, v4, v1
	v_add_u32_e32 v1, v4, v1
	v_mul_hi_u32 v1, v5, v1
	v_mul_lo_u32 v3, v1, v2
	v_sub_u32_e32 v3, v5, v3
	v_add_u32_e32 v4, 1, v1
	v_cmp_ge_u32_e32 vcc, v3, v2
	s_nop 1
	v_cndmask_b32_e32 v1, v1, v4, vcc
	v_sub_u32_e32 v4, v3, v2
	v_cndmask_b32_e32 v3, v3, v4, vcc
	v_add_u32_e32 v4, 1, v1
	v_cmp_ge_u32_e32 vcc, v3, v2
	v_add_u32_e32 v3, 1, v5
	s_nop 0
	v_cndmask_b32_e32 v1, v1, v4, vcc
	v_mul_lo_u32 v4, v2, v1
	v_add_u32_e32 v2, v4, v2
	v_cmp_ne_u32_e32 vcc, v3, v2
	s_and_saveexec_b64 s[8:9], vcc
	s_xor_b64 s[8:9], exec, s[8:9]
	s_cbranch_execz .LBB0_799
	s_waitcnt lgkmcnt(0)
	v_add_u32_e32 v4, 1, v1
	v_mul_lo_u32 v4, v4, v0
	v_mov_b32_e32 v5, 0x2303000
	v_mov_b32_e32 v0, 0x2000
	buffer_inv sc1
	global_load_dword v0, v5, s[70:71] offset:1024 sc1
	s_add_u32 s14, s6, 0x2400
	s_addc_u32 s15, s7, 0
	s_waitcnt vmcnt(0)
	v_cmp_lt_u32_e32 vcc, v0, v4
	s_and_saveexec_b64 s[10:11], vcc
	s_cbranch_execz .LBB0_798
	s_add_u32 s12, s70, 0x2300200
	s_addc_u32 s13, s71, 0
	s_mov_b32 s3, 1
	s_mov_b64 s[18:19], 0
	v_mov_b32_e32 v0, 0
	s_branch .LBB0_789

.LBB0_793:
	global_load_dword v2, v5, s[70:71] offset:1024 sc1
	s_add_i32 s3, s3, 1
	s_mov_b64 s[24:25], -1
	s_waitcnt vmcnt(0)
	v_cmp_ge_u32_e32 vcc, v2, v4
	s_orn2_b64 s[22:23], vcc, exec
	s_branch .LBB0_788
